# GEMM prologues: K-tile-1 staging loads issued before waiting for K-tile 0 (8 gemm_phase calls), on v38
# speedup vs baseline: 1.0032x; 1.0032x over previous
.LBB0_190:
	s_add_u32 s6, s66, 0xd1800
	s_addc_u32 s7, s67, 0
	s_add_u32 s8, s66, 0xa8c00
	s_addc_u32 s9, s67, 0
	s_add_u32 s10, s66, 0x25f00000
	s_addc_u32 s11, s67, 0
	s_lshl_b32 s12, s12, 5
	s_and_b32 s18, s12, 0x60
	s_mov_b64 s[12:13], 0x80
	s_add_i32 m0, s25, 0x18000
	v_lshl_add_u64 v[8:9], v[8:9], 0, s[12:13]
	s_lshl_b32 s15, s14, 13
	global_load_lds_dwordx4 v[8:9], off
	v_lshl_add_u64 v[6:7], v[6:7], 0, s[12:13]
	s_add_i32 m0, s25, 0x1a000
	s_add_i32 s43, s25, 0x8000
	s_add_i32 s44, s25, 0xa000
	global_load_lds_dwordx4 v[6:7], off
	v_lshl_add_u64 v[2:3], v[2:3], 0, s[12:13]
	s_mov_b32 m0, s43
	s_add_u32 s16, s28, 0x80080
	global_load_lds_dwordx4 v[2:3], off
	v_lshl_add_u64 v[2:3], v[4:5], 0, s[12:13]
	s_mov_b32 m0, s44
	s_addc_u32 s17, s29, 0
	global_load_lds_dwordx4 v[2:3], off
	s_add_i32 m0, s25, 0x1c000
	v_lshl_add_u64 v[2:3], s[16:17], 0, v[132:133]
	global_load_lds_dwordx4 v[2:3], off
	v_lshl_add_u64 v[2:3], s[16:17], 0, v[136:137]
	s_add_i32 m0, s25, 0x1e000
	v_lshlrev_b32_e32 v4, 12, v155
	global_load_lds_dwordx4 v[2:3], off
	s_waitcnt vmcnt(8)
	s_barrier
	v_lshlrev_b32_e32 v3, 2, v161
	v_lshl_or_b32 v2, v161, 6, v163
	v_and_b32_e32 v3, 32, v3
	v_bitop3_b32 v2, v2, s15, v3 bitop3:0xde
	v_lshlrev_b32_e32 v3, 9, v0
	v_and_b32_e32 v3, 0x30000, v3
	v_or3_b32 v3, v1, v3, v4
	v_add_u32_e32 v138, v3, v153
	v_lshlrev_b32_e32 v3, 5, v157
	s_waitcnt vmcnt(6)
	s_cmpk_lt_u32 s5, 0x100
	v_and_b32_e32 v3, 0x70000, v3
	v_lshl_or_b32 v171, s14, 6, v161
	v_lshl_or_b32 v172, s18, 7, v165
	s_cselect_b64 s[14:15], -1, 0
	v_or3_b32 v3, v1, v3, v4
	s_add_i32 s45, 0, 0x10000
	s_add_i32 s46, 0, 0x14000
	s_sext_i32_i16 s48, s4
	v_or_b32_e32 v173, s18, v159
	v_mov_b32_e32 v139, v133
	v_add_u32_e32 v140, v3, v153
	v_mov_b32_e32 v141, v133
	v_mov_b64_e32 v[142:143], 0x8e3
	v_mov_b64_e32 v[144:145], 0x8e2
	v_add_u32_e32 v174, s45, v172
	v_add_u32_e32 v175, s46, v172
	v_add_u32_e32 v176, 0, v2
	s_movk_i32 s47, 0x5a00
	s_barrier
	s_branch .LBB0_193

.LBB0_210:
	s_lshl_b32 s6, s6, 5
	s_lshl_b32 s11, s10, 13
	s_and_b32 s14, s6, 0x60
	s_add_u32 s6, s66, 0x25f04600
	s_mov_b64 s[8:9], 0x80
	s_addc_u32 s7, s67, 0
	s_add_i32 m0, s21, 0x18000
	v_lshl_add_u64 v[8:9], v[8:9], 0, s[8:9]
	global_load_lds_dwordx4 v[8:9], off
	v_lshl_add_u64 v[6:7], v[6:7], 0, s[8:9]
	s_add_i32 m0, s21, 0x1a000
	s_add_i32 s39, s21, 0x8000
	s_add_i32 s40, s21, 0xa000
	global_load_lds_dwordx4 v[6:7], off
	v_lshl_add_u64 v[2:3], v[2:3], 0, s[8:9]
	s_mov_b32 m0, s39
	s_add_u32 s12, s24, 0x100080
	global_load_lds_dwordx4 v[2:3], off
	v_lshl_add_u64 v[2:3], v[4:5], 0, s[8:9]
	s_mov_b32 m0, s40
	s_addc_u32 s13, s25, 0
	global_load_lds_dwordx4 v[2:3], off
	s_add_i32 m0, s21, 0x1c000
	v_lshl_add_u64 v[2:3], s[12:13], 0, v[132:133]
	global_load_lds_dwordx4 v[2:3], off
	v_lshl_add_u64 v[2:3], s[12:13], 0, v[136:137]
	s_add_i32 m0, s21, 0x1e000
	v_lshlrev_b32_e32 v4, 13, v155
	global_load_lds_dwordx4 v[2:3], off
	s_waitcnt vmcnt(8)
	s_barrier
	v_lshlrev_b32_e32 v3, 2, v161
	v_lshl_or_b32 v2, v161, 6, v163
	v_and_b32_e32 v3, 32, v3
	v_bitop3_b32 v2, v2, s11, v3 bitop3:0xde
	v_lshlrev_b32_e32 v3, 10, v0
	v_and_b32_e32 v3, 0x60000, v3
	v_or3_b32 v3, v1, v3, v4
	v_add_u32_e32 v138, v3, v153
	v_lshlrev_b32_e32 v3, 6, v157
	s_waitcnt vmcnt(6)
	s_cmpk_lt_u32 s5, 0x100
	v_and_b32_e32 v3, 0xe0000, v3
	v_lshl_or_b32 v150, s10, 6, v161
	v_lshl_or_b32 v151, s14, 7, v165
	s_cselect_b64 s[10:11], -1, 0
	v_or3_b32 v1, v1, v3, v4
	s_add_i32 s41, 0, 0x10000
	s_add_i32 s42, 0, 0x14000
	s_sext_i32_i8 s44, s4
	v_or_b32_e32 v152, s14, v159
	v_mov_b32_e32 v139, v133
	v_add_u32_e32 v140, v1, v153
	v_mov_b32_e32 v141, v133
	v_mov_b64_e32 v[142:143], 0x28a
	v_mov_b64_e32 v[144:145], 0x289
	v_add_u32_e32 v1, s41, v151
	v_add_u32_e32 v153, s42, v151
	v_add_u32_e32 v154, 0, v2
	s_movk_i32 s43, 0x5a00
	s_barrier
	s_branch .LBB0_213

.LBB0_1472:
	s_lshl_b32 s6, s6, 5
	s_and_b32 s18, s6, 0x60
	s_lshl_b32 s15, s14, 13
	s_lshl_b32 s19, s18, 7
	s_add_u32 s6, s66, 0xd1840
	s_addc_u32 s7, s67, 0
	s_add_u32 s8, s66, 0xb4000
	s_addc_u32 s9, s67, 0
	s_add_u32 s10, s66, 0x25f40000
	s_mov_b64 s[12:13], 0x80
	s_addc_u32 s11, s67, 0
	s_add_i32 m0, s31, 0x18000
	v_lshl_add_u64 v[8:9], v[8:9], 0, s[12:13]
	global_load_lds_dwordx4 v[8:9], off
	v_lshl_add_u64 v[6:7], v[6:7], 0, s[12:13]
	s_add_i32 m0, s31, 0x1a000
	s_add_i32 s49, s31, 0x8000
	s_add_i32 s50, s31, 0xa000
	global_load_lds_dwordx4 v[6:7], off
	v_lshl_add_u64 v[2:3], v[2:3], 0, s[12:13]
	s_mov_b32 m0, s49
	s_add_u32 s16, s36, 0x80080
	global_load_lds_dwordx4 v[2:3], off
	v_lshl_add_u64 v[2:3], v[4:5], 0, s[12:13]
	s_mov_b32 m0, s50
	s_addc_u32 s17, s37, 0
	global_load_lds_dwordx4 v[2:3], off
	s_add_i32 m0, s31, 0x1c000
	v_lshl_add_u64 v[2:3], s[16:17], 0, v[132:133]
	global_load_lds_dwordx4 v[2:3], off
	v_lshl_add_u64 v[2:3], s[16:17], 0, v[136:137]
	s_add_i32 m0, s31, 0x1e000
	s_sext_i32_i8 s33, s4
	global_load_lds_dwordx4 v[2:3], off
	s_waitcnt vmcnt(8)
	s_barrier
	v_lshlrev_b32_e32 v2, 1, v13
	v_lshlrev_b32_e32 v1, 6, v0
	s_movk_i32 s4, 0x3c0
	v_and_or_b32 v3, v1, s4, v2
	v_lshlrev_b32_e32 v1, 2, v0
	v_and_b32_e32 v4, 32, v1
	v_bitop3_b32 v153, s19, v3, v4 bitop3:0xf6
	v_lshlrev_b32_e32 v3, 9, v0
	v_and_b32_e32 v3, 0x30000, v3
	v_lshlrev_b32_e32 v4, 12, v12
	v_or3_b32 v3, v10, v3, v4
	v_lshlrev_b32_e32 v5, 2, v90
	v_add_u32_e32 v138, v3, v11
	v_lshlrev_b32_e32 v3, 5, v14
	v_lshl_or_b32 v2, v90, 6, v2
	v_and_b32_e32 v5, 32, v5
	s_waitcnt vmcnt(6)
	s_cmpk_lt_u32 s5, 0x100
	v_and_b32_e32 v3, 0x70000, v3
	v_lshl_or_b32 v1, s14, 6, v90
	v_bitop3_b32 v2, v2, s15, v5 bitop3:0xde
	s_cselect_b64 s[14:15], -1, 0
	v_or3_b32 v3, v10, v3, v4
	s_add_i32 s51, 0, 0x10000
	s_add_i32 s54, 0, 0x14000
	v_or_b32_e32 v155, s18, v13
	v_mov_b32_e32 v139, v133
	v_add_u32_e32 v140, v3, v11
	v_mov_b32_e32 v141, v133
	v_mov_b64_e32 v[142:143], 0x800
	v_mov_b64_e32 v[144:145], 0x7ff
	v_add_u32_e32 v157, s51, v153
	v_add_u32_e32 v159, s54, v153
	v_add_u32_e32 v161, 0, v2
	s_mov_b64 s[16:17], 0x240000
	s_mov_b32 s55, 0x240000
	s_mov_b64 s[18:19], 0x280000
	s_mov_b32 s60, 0x280000
	s_mov_b64 s[20:21], 0x2c0000
	s_mov_b32 s61, 0x2c0000
	s_barrier
	s_branch .LBB0_1475

.LBB0_1552:
	s_add_u32 s6, s66, 0x3ccc0000
	s_addc_u32 s7, s67, 0
	s_add_u32 s8, s66, 0x25f40000
	s_addc_u32 s9, s67, 0
	s_lshl_b32 s10, s10, 5
	s_and_b32 s16, s10, 0x60
	s_mov_b64 s[10:11], 0x80
	s_add_i32 m0, s23, 0x18000
	v_lshl_add_u64 v[8:9], v[8:9], 0, s[10:11]
	s_ashr_i32 s40, s84, 31
	s_lshl_b32 s13, s12, 13
	s_lshl_b32 s17, s16, 7
	global_load_lds_dwordx4 v[8:9], off
	v_lshl_add_u64 v[6:7], v[6:7], 0, s[10:11]
	s_add_i32 m0, s23, 0x1a000
	s_add_i32 s41, s23, 0x8000
	s_add_i32 s42, s23, 0xa000
	global_load_lds_dwordx4 v[6:7], off
	v_lshl_add_u64 v[2:3], v[2:3], 0, s[10:11]
	s_mov_b32 m0, s41
	s_add_u32 s14, s26, 0x80080
	global_load_lds_dwordx4 v[2:3], off
	v_lshl_add_u64 v[2:3], v[4:5], 0, s[10:11]
	s_mov_b32 m0, s42
	s_addc_u32 s15, s27, 0
	global_load_lds_dwordx4 v[2:3], off
	s_add_i32 m0, s23, 0x1c000
	v_lshl_add_u64 v[2:3], s[14:15], 0, v[132:133]
	global_load_lds_dwordx4 v[2:3], off
	v_lshl_add_u64 v[2:3], s[14:15], 0, v[136:137]
	s_add_i32 m0, s23, 0x1e000
	s_sext_i32_i8 s45, s4
	global_load_lds_dwordx4 v[2:3], off
	s_waitcnt vmcnt(8)
	s_barrier
	v_lshlrev_b32_e32 v3, 1, v13
	v_lshlrev_b32_e32 v1, 6, v0
	s_movk_i32 s4, 0x3c0
	v_and_b32_e32 v2, 15, v0
	v_and_or_b32 v4, v1, s4, v3
	v_lshlrev_b32_e32 v1, 2, v0
	v_and_b32_e32 v5, 32, v1
	v_lshl_or_b32 v1, s12, 6, v2
	v_lshl_or_b32 v2, v2, 6, v3
	v_lshlrev_b32_e32 v3, 9, v0
	v_bitop3_b32 v150, s17, v4, v5 bitop3:0xf6
	v_and_b32_e32 v3, 0x30000, v3
	v_lshlrev_b32_e32 v4, 12, v12
	v_or3_b32 v3, v10, v3, v4
	v_add_u32_e32 v138, v3, v11
	v_lshlrev_b32_e32 v3, 5, v14
	s_waitcnt vmcnt(6)
	s_cmpk_lt_u32 s5, 0x100
	v_and_b32_e32 v3, 0x70000, v3
	v_bitop3_b32 v2, v2, s13, v5 bitop3:0xde
	s_cselect_b64 s[12:13], -1, 0
	v_or3_b32 v3, v10, v3, v4
	s_add_i32 s43, 0, 0x10000
	s_add_i32 s44, 0, 0x14000
	v_or_b32_e32 v151, s16, v13
	v_mov_b32_e32 v139, v133
	v_add_u32_e32 v140, v3, v11
	v_mov_b32_e32 v141, v133
	v_mov_b64_e32 v[142:143], 0x400
	v_mov_b64_e32 v[144:145], 0x3ff
	v_add_u32_e32 v152, s43, v150
	v_add_u32_e32 v153, s44, v150
	v_add_u32_e32 v154, 0, v2
	s_barrier
	s_branch .LBB0_1555

.LBB0_1632:
	s_add_u32 s6, s66, 0x1dd20000
	s_addc_u32 s7, s67, 0
	s_add_u32 s8, s66, 0x3ccc0000
	s_addc_u32 s9, s67, 0
	s_add_u32 s10, s66, 0x25f40000
	s_addc_u32 s11, s67, 0
	s_lshl_b32 s12, s12, 5
	s_and_b32 s18, s12, 0x60
	s_mov_b64 s[12:13], 0x80
	s_add_i32 m0, s27, 0x18000
	v_lshl_add_u64 v[8:9], v[8:9], 0, s[12:13]
	s_ashr_i32 s45, s84, 31
	s_lshl_b32 s15, s14, 13
	s_lshl_b32 s19, s18, 7
	global_load_lds_dwordx4 v[8:9], off
	v_lshl_add_u64 v[6:7], v[6:7], 0, s[12:13]
	s_add_i32 m0, s27, 0x1a000
	s_add_i32 s46, s27, 0x8000
	s_add_i32 s47, s27, 0xa000
	global_load_lds_dwordx4 v[6:7], off
	v_lshl_add_u64 v[2:3], v[2:3], 0, s[12:13]
	s_mov_b32 m0, s46
	s_add_u32 s16, s30, 0x80080
	global_load_lds_dwordx4 v[2:3], off
	v_lshl_add_u64 v[2:3], v[4:5], 0, s[12:13]
	s_mov_b32 m0, s47
	s_addc_u32 s17, s31, 0
	global_load_lds_dwordx4 v[2:3], off
	s_add_i32 m0, s27, 0x1c000
	v_lshl_add_u64 v[2:3], s[16:17], 0, v[132:133]
	global_load_lds_dwordx4 v[2:3], off
	v_lshl_add_u64 v[2:3], s[16:17], 0, v[136:137]
	s_add_i32 m0, s27, 0x1e000
	s_sext_i32_i8 s50, s4
	global_load_lds_dwordx4 v[2:3], off
	s_waitcnt vmcnt(8)
	s_barrier
	v_lshlrev_b32_e32 v3, 1, v13
	v_lshlrev_b32_e32 v1, 6, v0
	s_movk_i32 s4, 0x3c0
	v_and_b32_e32 v2, 15, v0
	v_and_or_b32 v4, v1, s4, v3
	v_lshlrev_b32_e32 v1, 2, v0
	v_and_b32_e32 v5, 32, v1
	v_lshl_or_b32 v1, s14, 6, v2
	v_lshl_or_b32 v2, v2, 6, v3
	v_lshlrev_b32_e32 v3, 9, v0
	v_bitop3_b32 v150, s19, v4, v5 bitop3:0xf6
	v_and_b32_e32 v3, 0x30000, v3
	v_lshlrev_b32_e32 v4, 12, v12
	v_or3_b32 v3, v10, v3, v4
	v_add_u32_e32 v138, v3, v11
	v_lshlrev_b32_e32 v3, 5, v14
	s_waitcnt vmcnt(6)
	s_cmpk_lt_u32 s5, 0x100
	v_and_b32_e32 v3, 0x70000, v3
	v_bitop3_b32 v2, v2, s15, v5 bitop3:0xde
	s_cselect_b64 s[14:15], -1, 0
	v_or3_b32 v3, v10, v3, v4
	s_add_i32 s48, 0, 0x10000
	s_add_i32 s49, 0, 0x14000
	v_or_b32_e32 v151, s18, v13
	v_mov_b32_e32 v139, v133
	v_add_u32_e32 v140, v3, v11
	v_mov_b32_e32 v141, v133
	v_mov_b64_e32 v[142:143], 0x400
	v_mov_b64_e32 v[144:145], 0x3ff
	v_add_u32_e32 v152, s48, v150
	v_add_u32_e32 v153, s49, v150
	v_add_u32_e32 v154, 0, v2
	s_mov_b64 s[16:17], 0x2000
	s_barrier
	s_branch .LBB0_1635

.LBB0_1712:
	s_add_u32 s6, s66, 0x2ff00000
	s_addc_u32 s7, s67, 0
	s_lshl_b32 s8, s8, 5
	s_and_b32 s14, s8, 0x60
	s_mov_b64 s[8:9], 0x80
	s_add_i32 m0, s29, 0x18000
	v_lshl_add_u64 v[8:9], v[8:9], 0, s[8:9]
	s_ashr_i32 s46, s84, 31
	s_lshl_b32 s11, s10, 13
	s_lshl_b32 s15, s14, 7
	global_load_lds_dwordx4 v[8:9], off
	v_lshl_add_u64 v[6:7], v[6:7], 0, s[8:9]
	s_add_i32 m0, s29, 0x1a000
	s_add_i32 s47, s29, 0x8000
	s_add_i32 s48, s29, 0xa000
	global_load_lds_dwordx4 v[6:7], off
	v_lshl_add_u64 v[2:3], v[2:3], 0, s[8:9]
	s_mov_b32 m0, s47
	s_add_u32 s12, s34, 0x100080
	global_load_lds_dwordx4 v[2:3], off
	v_lshl_add_u64 v[2:3], v[4:5], 0, s[8:9]
	s_mov_b32 m0, s48
	s_addc_u32 s13, s35, 0
	global_load_lds_dwordx4 v[2:3], off
	s_add_i32 m0, s29, 0x1c000
	v_lshl_add_u64 v[2:3], s[12:13], 0, v[132:133]
	global_load_lds_dwordx4 v[2:3], off
	v_lshl_add_u64 v[2:3], s[12:13], 0, v[136:137]
	s_add_i32 m0, s29, 0x1e000
	s_sext_i32_i8 s51, s4
	global_load_lds_dwordx4 v[2:3], off
	s_waitcnt vmcnt(8)
	s_barrier
	v_lshlrev_b32_e32 v3, 1, v13
	v_lshlrev_b32_e32 v1, 6, v0
	s_movk_i32 s4, 0x3c0
	v_and_b32_e32 v2, 15, v0
	v_and_or_b32 v4, v1, s4, v3
	v_lshlrev_b32_e32 v1, 2, v0
	v_and_b32_e32 v5, 32, v1
	v_lshl_or_b32 v1, s10, 6, v2
	v_lshl_or_b32 v2, v2, 6, v3
	v_lshlrev_b32_e32 v3, 10, v0
	v_bitop3_b32 v152, s15, v4, v5 bitop3:0xf6
	v_and_b32_e32 v3, 0x60000, v3
	v_lshlrev_b32_e32 v4, 13, v12
	v_or3_b32 v3, v10, v3, v4
	v_add_u32_e32 v138, v3, v11
	v_lshlrev_b32_e32 v3, 6, v14
	s_waitcnt vmcnt(6)
	s_cmpk_lt_u32 s5, 0x100
	v_and_b32_e32 v3, 0xe0000, v3
	v_bitop3_b32 v2, v2, s11, v5 bitop3:0xde
	s_cselect_b64 s[10:11], -1, 0
	v_or3_b32 v3, v10, v3, v4
	s_add_i32 s49, 0, 0x10000
	s_add_i32 s50, 0, 0x14000
	v_or_b32_e32 v153, s14, v13
	v_mov_b32_e32 v139, v133
	v_add_u32_e32 v140, v3, v11
	v_mov_b32_e32 v141, v133
	v_mov_b64_e32 v[142:143], 0x400
	v_mov_b64_e32 v[144:145], 0x3ff
	v_add_u32_e32 v154, s49, v152
	v_add_u32_e32 v155, s50, v152
	v_add_u32_e32 v156, 0, v2
	s_mov_b64 s[12:13], 0x80000
	s_mov_b64 s[14:15], 0x90000
	s_mov_b64 s[16:17], 0xa0000
	s_mov_b64 s[18:19], 0xb0000
	s_barrier
	s_branch .LBB0_1715

.LBB0_1866:
	s_add_u32 s12, s66, 0x3bc60000
	s_addc_u32 s13, s67, 0
	s_add_u32 s14, s66, 0x25f00000
	s_addc_u32 s15, s67, 0
	s_add_u32 s16, s66, 0xe1d00
	s_addc_u32 s17, s67, 0
	s_lshl_b32 s4, s4, 5
	s_mov_b64 s[18:19], 0x80
	s_and_b32 s22, s4, 0x60
	s_add_i32 m0, s51, 0x18000
	v_lshl_add_u64 v[8:9], v[8:9], 0, s[18:19]
	s_lshl_b32 s28, s11, 11
	s_ashr_i32 s60, s84, 31
	s_add_i32 s29, 0, 0x20000
	s_lshl_b32 s20, s11, 13
	s_lshl_b32 s21, s22, 7
	global_load_lds_dwordx4 v[8:9], off
	v_lshl_add_u64 v[6:7], v[6:7], 0, s[18:19]
	s_add_i32 m0, s51, 0x1a000
	s_add_i32 s61, s51, 0x8000
	s_add_i32 s68, s51, 0xa000
	global_load_lds_dwordx4 v[6:7], off
	v_lshl_add_u64 v[2:3], v[2:3], 0, s[18:19]
	s_mov_b32 m0, s61
	s_add_u32 s4, s44, 0x80080
	global_load_lds_dwordx4 v[2:3], off
	v_lshl_add_u64 v[2:3], v[4:5], 0, s[18:19]
	s_mov_b32 m0, s68
	s_addc_u32 s5, s45, 0
	global_load_lds_dwordx4 v[2:3], off
	s_add_i32 m0, s51, 0x1c000
	v_lshl_add_u64 v[2:3], s[4:5], 0, v[182:183]
	global_load_lds_dwordx4 v[2:3], off
	v_lshl_add_u64 v[2:3], s[4:5], 0, v[186:187]
	s_add_i32 m0, s51, 0x1e000
	v_lshlrev_b32_e32 v1, 6, v0
	global_load_lds_dwordx4 v[2:3], off
	s_waitcnt vmcnt(8)
	s_barrier
	v_lshlrev_b32_e32 v2, 1, v14
	s_movk_i32 s4, 0x3c0
	v_and_b32_e32 v190, 15, v0
	v_and_or_b32 v3, v1, s4, v2
	v_lshlrev_b32_e32 v1, 2, v0
	v_and_b32_e32 v4, 32, v1
	v_cmp_lt_u32_e64 s[4:5], 13, v190
	v_lshl_or_b32 v2, v190, 6, v2
	s_cmpk_lt_u32 s10, 0x100
	v_cmp_gt_u32_e64 s[6:7], 2, v190
	v_bitop3_b32 v7, v2, s20, v4 bitop3:0xde
	v_bitop3_b32 v191, s21, v3, v4 bitop3:0xf6
	s_cselect_b64 s[20:21], -1, 0
	s_and_b64 s[24:25], s[4:5], s[0:1]
	v_or_b32_e32 v194, s22, v14
	s_and_b64 s[22:23], s[20:21], s[6:7]
	s_xor_b64 s[24:25], s[24:25], -1
	s_cmpk_gt_u32 s10, 0xff
	v_lshlrev_b32_e32 v5, 10, v190
	v_lshl_or_b32 v1, s11, 6, v190
	s_cselect_b64 s[10:11], -1, 0
	v_lshlrev_b32_e32 v188, 2, v194
	v_add_u32_e32 v6, s28, v5
	s_and_b64 s[26:27], s[4:5], s[10:11]
	v_lshl_add_u64 v[2:3], s[66:67], 0, v[188:189]
	s_mov_b64 s[10:11], 0xbc000
	s_add_i32 s28, s28, s29
	v_lshl_add_u64 v[196:197], v[2:3], 0, s[10:11]
	v_add3_u32 v2, s28, v5, v188
	v_add_u32_e32 v215, 0xffffc000, v2
	v_add_u32_e32 v216, 0xffffd000, v2
	v_add_u32_e32 v217, 0xffffc010, v2
	v_add_u32_e32 v218, 0xffffd010, v2
	v_lshlrev_b32_e32 v2, 9, v0
	v_and_b32_e32 v2, 0x30000, v2
	v_lshlrev_b32_e32 v3, 12, v12
	v_or3_b32 v2, v10, v2, v3
	v_add_u32_e32 v198, v2, v11
	v_lshlrev_b32_e32 v2, 5, v13
	s_waitcnt vmcnt(6)
	v_and_b32_e32 v2, 0x70000, v2
	v_add_u32_e32 v4, 0xffffc800, v6
	s_add_i32 s10, 0, 0x21000
	v_or3_b32 v2, v10, v2, v3
	s_add_i32 s69, 0, 0x10000
	s_add_i32 s70, 0, 0x14000
	v_add_u32_e32 v192, -12, v190
	v_mov_b32_e32 v193, v189
	v_cmp_eq_u32_e64 s[8:9], 0, v190
	v_add3_u32 v195, s29, v4, v188
	v_add3_u32 v214, s10, v4, v188
	v_mov_b32_e32 v199, v189
	v_add_u32_e32 v200, v2, v11
	v_mov_b32_e32 v201, v189
	v_mov_b64_e32 v[202:203], 0x15d6
	v_mov_b64_e32 v[204:205], 0x15d5
	v_add_u32_e32 v219, s69, v191
	v_add_u32_e32 v220, s70, v191
	v_add_u32_e32 v221, 0, v7
	s_mov_b32 s71, 0x15800
	s_movk_i32 s72, 0x5600
	v_mov_b32_e32 v222, 0x15800
	s_barrier
	s_branch .LBB0_1869

.LBB0_2026:
	s_add_u32 s8, s66, 0x2ff00000
	s_addc_u32 s9, s67, 0
	s_add_u32 s10, s66, 0x25f00000
	s_addc_u32 s11, s67, 0
	s_lshl_b32 s7, s7, 5
	s_mov_b64 s[12:13], 0x80
	s_and_b32 s7, s7, 0x60
	s_add_i32 m0, s38, 0x18000
	v_lshl_add_u64 v[8:9], v[8:9], 0, s[12:13]
	s_ashr_i32 s43, s84, 31
	s_lshl_b32 s16, s5, 13
	s_lshl_b32 s17, s7, 7
	global_load_lds_dwordx4 v[8:9], off
	v_lshl_add_u64 v[6:7], v[6:7], 0, s[12:13]
	s_add_i32 m0, s38, 0x1a000
	s_add_i32 s44, s38, 0x8000
	s_add_i32 s45, s38, 0xa000
	global_load_lds_dwordx4 v[6:7], off
	v_lshl_add_u64 v[2:3], v[2:3], 0, s[12:13]
	s_mov_b32 m0, s44
	s_add_u32 s14, s28, 0x2b0080
	global_load_lds_dwordx4 v[2:3], off
	v_lshl_add_u64 v[2:3], v[4:5], 0, s[12:13]
	s_mov_b32 m0, s45
	s_addc_u32 s15, s29, 0
	global_load_lds_dwordx4 v[2:3], off
	s_add_i32 m0, s38, 0x1c000
	v_lshl_add_u64 v[2:3], s[14:15], 0, v[132:133]
	global_load_lds_dwordx4 v[2:3], off
	v_lshl_add_u64 v[2:3], s[14:15], 0, v[136:137]
	s_add_i32 m0, s38, 0x1e000
	s_sext_i32_i8 s51, s6
	global_load_lds_dwordx4 v[2:3], off
	s_waitcnt vmcnt(8)
	s_barrier
	v_lshlrev_b32_e32 v3, 1, v12
	v_lshlrev_b32_e32 v1, 6, v0
	s_movk_i32 s6, 0x3c0
	v_and_b32_e32 v2, 15, v0
	v_and_or_b32 v4, v1, s6, v3
	v_lshlrev_b32_e32 v1, 2, v0
	v_and_b32_e32 v5, 32, v1
	v_lshl_or_b32 v1, s5, 6, v2
	v_lshl_or_b32 v2, v2, 6, v3
	s_waitcnt vmcnt(6)
	s_cmpk_lt_u32 s4, 0x100
	v_add_u16_e32 v3, v10, v11
	v_bitop3_b32 v2, v2, s16, v5 bitop3:0xde
	v_bitop3_b32 v152, s17, v4, v5 bitop3:0xf6
	s_cselect_b64 s[14:15], -1, 0
	v_lshrrev_b16_e32 v3, 1, v3
	s_add_i32 s46, 0, 0x10000
	s_add_i32 s47, 0, 0x14000
	v_or_b32_e32 v153, s7, v12
	v_add_lshl_u32 v138, v13, v3, 1
	v_mov_b32_e32 v139, v133
	v_add_lshl_u32 v140, v14, v3, 1
	v_mov_b32_e32 v141, v133
	v_mov_b64_e32 v[142:143], 0x400
	v_mov_b64_e32 v[144:145], 0x3ff
	v_add_u32_e32 v154, s46, v152
	v_add_u32_e32 v155, s47, v152
	v_add_u32_e32 v156, 0, v2
	s_mov_b64 s[16:17], 0x100000
	s_mov_b64 s[18:19], 0x120000
	s_mov_b64 s[20:21], 0x140000
	s_mov_b64 s[22:23], 0x160000
	s_barrier
	s_branch .LBB0_2029
